# attention row-max cross-half exchange via v_permlane32_swap instead of ds_bpermute (on top of the EpiResid permlane reduction)
# baseline (speedup 1.0000x reference)
; __device__ __forceinline__ void attn_phase(LAS unsigned char* lds, const bf16* Q, const bf16* KV, const bf16* KPE, const float* rope, bf16* mix, int bid, int G, int tid) {
;     ...
;                 float mx = fmaxf(S0[0], S1[0]);
; #pragma unroll
;                 for (int e = 1; e < 16; ++e) mx = fmaxf(mx, fmaxf(S0[e], S1[e]));
;                 mx = fmaxf(mx, __shfl_xor(mx, 32));
;                 const float mnew = (mx > mrun + 6.0f) ? mx : mrun;
;                 const float alpha = __builtin_amdgcn_exp2f(mrun - mnew); mrun = mnew;
;                 float rs = 0.f;
; #pragma unroll
;                 for (int e = 0; e < 16; ++e) { S0[e] = __builtin_amdgcn_exp2f(S0[e] - mnew); S1[e] = __builtin_amdgcn_exp2f(S1[e] - mnew); rs += S0[e] + S1[e]; }
;                 lrun = lrun * alpha + rs;
;                 if (__builtin_amdgcn_ballot_w64(alpha != 1.0f) != 0ull) {
; #pragma unroll
;                     for (int i = 0; i < 4; ++i)
; #pragma unroll
;                         for (int e = 0; e < 16; ++e) O[i][e] *= alpha; }
.LBB0_256:
	s_nop 9
	v_max3_f32 v209, v64, v65, v66
	v_max3_f32 v210, v67, v68, v69
	v_max3_f32 v211, v70, v71, v72
	v_max3_f32 v212, v73, v74, v75
	v_max3_f32 v209, v209, v76, v77
	v_max3_f32 v210, v210, v78, v79
	v_max3_f32 v211, v211, v80, v81
	v_max3_f32 v212, v212, v82, v83
	v_max3_f32 v209, v209, v84, v85
	v_max3_f32 v210, v210, v86, v87
	v_max3_f32 v211, v211, v88, v89
	v_max3_f32 v212, v212, v90, v91
	v_max3_f32 v209, v209, v92, v93
	v_max3_f32 v210, v210, v94, v95
	v_max3_f32 v209, v209, v210, v211
	v_max_f32_e32 v209, v209, v212
	v_mov_b32_e32 v210, v209
	s_nop 1
	v_permlane32_swap_b32_e32 v209, v210
	s_waitcnt lgkmcnt(0)
	v_max_f32_e32 v210, v210, v210
	v_max_f32_e32 v209, v209, v210
	v_add_f32_e32 v210, 0x40c00000, v184
	v_cmp_gt_f32_e32 vcc, v209, v210
	s_nop 1
	v_cndmask_b32_e32 v209, v184, v209, vcc
	v_sub_f32_e32 v184, v184, v209
	v_exp_f32_e32 v184, v184
	s_nop 0
	v_cmp_neq_f32_e32 vcc, 1.0, v184
	s_cbranch_vccz .LBB0_258
	v_pk_mul_f32 v[62:63], v[62:63], v[184:185] op_sel_hi:[1,0]
	v_pk_mul_f32 v[60:61], v[60:61], v[184:185] op_sel_hi:[1,0]
	v_pk_mul_f32 v[58:59], v[58:59], v[184:185] op_sel_hi:[1,0]
	v_pk_mul_f32 v[56:57], v[56:57], v[184:185] op_sel_hi:[1,0]
	v_pk_mul_f32 v[54:55], v[54:55], v[184:185] op_sel_hi:[1,0]
	v_pk_mul_f32 v[52:53], v[52:53], v[184:185] op_sel_hi:[1,0]
	v_pk_mul_f32 v[50:51], v[50:51], v[184:185] op_sel_hi:[1,0]
	v_pk_mul_f32 v[48:49], v[48:49], v[184:185] op_sel_hi:[1,0]
	v_pk_mul_f32 v[46:47], v[46:47], v[184:185] op_sel_hi:[1,0]
	v_pk_mul_f32 v[44:45], v[44:45], v[184:185] op_sel_hi:[1,0]
	v_pk_mul_f32 v[42:43], v[42:43], v[184:185] op_sel_hi:[1,0]
	v_pk_mul_f32 v[40:41], v[40:41], v[184:185] op_sel_hi:[1,0]
	v_pk_mul_f32 v[38:39], v[38:39], v[184:185] op_sel_hi:[1,0]
	v_pk_mul_f32 v[36:37], v[36:37], v[184:185] op_sel_hi:[1,0]
	v_pk_mul_f32 v[34:35], v[34:35], v[184:185] op_sel_hi:[1,0]
	v_pk_mul_f32 v[32:33], v[32:33], v[184:185] op_sel_hi:[1,0]
	v_pk_mul_f32 v[30:31], v[30:31], v[184:185] op_sel_hi:[1,0]
	v_pk_mul_f32 v[28:29], v[28:29], v[184:185] op_sel_hi:[1,0]
	v_pk_mul_f32 v[26:27], v[26:27], v[184:185] op_sel_hi:[1,0]
	v_pk_mul_f32 v[24:25], v[24:25], v[184:185] op_sel_hi:[1,0]
	v_pk_mul_f32 v[22:23], v[22:23], v[184:185] op_sel_hi:[1,0]
	v_pk_mul_f32 v[20:21], v[20:21], v[184:185] op_sel_hi:[1,0]
	v_pk_mul_f32 v[18:19], v[18:19], v[184:185] op_sel_hi:[1,0]
	v_pk_mul_f32 v[16:17], v[16:17], v[184:185] op_sel_hi:[1,0]
	v_pk_mul_f32 v[14:15], v[14:15], v[184:185] op_sel_hi:[1,0]
	v_pk_mul_f32 v[12:13], v[12:13], v[184:185] op_sel_hi:[1,0]
	v_pk_mul_f32 v[10:11], v[10:11], v[184:185] op_sel_hi:[1,0]
	v_pk_mul_f32 v[8:9], v[8:9], v[184:185] op_sel_hi:[1,0]
	v_pk_mul_f32 v[6:7], v[6:7], v[184:185] op_sel_hi:[1,0]
	v_pk_mul_f32 v[4:5], v[4:5], v[184:185] op_sel_hi:[1,0]
	v_pk_mul_f32 v[2:3], v[2:3], v[184:185] op_sel_hi:[1,0]
	v_pk_mul_f32 v[0:1], v[0:1], v[184:185] op_sel_hi:[1,0]
